# grid barrier: the acquire L1 invalidate is issued when a workgroup arrives (nothing is loaded through L1 between arrival and release; polls are sc1), so its completion latency is hidden in the spin in
# speedup vs baseline: 1.0200x; 1.0180x over previous
; DI unsigned xb_ld(unsigned* p) { return __hip_atomic_load(p, __ATOMIC_RELAXED, __HIP_MEMORY_SCOPE_AGENT); }
; DI unsigned xb_add(unsigned* p, unsigned v) { return __hip_atomic_fetch_add(p, v, __ATOMIC_RELAXED, __HIP_MEMORY_SCOPE_AGENT); }
; #define XB_SPIN(cond, bar) do { unsigned _sp = 0; while (cond) { __builtin_amdgcn_s_sleep(1); \
;     if ((++_sp & 255u) == 0u) { if (xb_ld(&(bar)[XB_TMO])) break; if (_sp > XB_SPIN_CAP) { atomicAdd(&(bar)[XB_TMO], 1u); break; } } } } while (0)
; DI void xcd_barrier(const XcdBarrier& b) {
;     ...
;     const unsigned old = xb_add(&bar[XB_XSUB(b.x)], 1u);
;     const unsigned gen = old / nloc;
;     if (old + 1u == (gen + 1u) * nloc) {
;       __builtin_amdgcn_fence(__ATOMIC_RELEASE, "agent");
;       asm volatile("s_waitcnt vmcnt(0)" ::: "memory");
;       const unsigned og = xb_add(&bar[XB_TOP], 1u);
;       const unsigned tg = og / nx;
;       if (og + 1u == (tg + 1u) * nx) xb_add(&bar[XB_TOPGEN], 1u);
;       else XB_SPIN(xb_ld(&bar[XB_TOPGEN]) == tg, bar);
;       __builtin_amdgcn_fence(__ATOMIC_ACQUIRE, "agent");
;       xb_add(&bar[XB_XGEN(b.x)], 1u);
;       asm volatile("s_waitcnt vmcnt(0)" ::: "memory");
;     } else {
;       XB_SPIN(xb_ld(&bar[XB_XGEN(b.x)]) == gen, bar);
;       __builtin_amdgcn_fence(__ATOMIC_ACQUIRE, "agent");
;       asm volatile("s_waitcnt vmcnt(0)" ::: "memory");
.LBB0_279:
	s_or_b64 exec, exec, s[14:15]
	v_cvt_f32_u32_e32 v6, v4
	s_waitcnt vmcnt(0)
	v_readfirstlane_b32 s2, v5
	v_sub_u32_e32 v5, 0, v4
	v_rcp_iflag_f32_e32 v6, v6
	v_add_u32_e32 v7, s2, v3
	v_mul_f32_e32 v6, 0x4f7ffffe, v6
	v_cvt_u32_f32_e32 v6, v6
	v_mul_lo_u32 v3, v5, v6
	v_mul_hi_u32 v3, v6, v3
	v_add_u32_e32 v3, v6, v3
	v_mul_hi_u32 v3, v7, v3
	v_mul_lo_u32 v5, v3, v4
	v_sub_u32_e32 v5, v7, v5
	v_add_u32_e32 v6, 1, v3
	v_cmp_ge_u32_e32 vcc, v5, v4
	s_nop 1
	v_cndmask_b32_e32 v3, v3, v6, vcc
	v_sub_u32_e32 v6, v5, v4
	v_cndmask_b32_e32 v5, v5, v6, vcc
	v_add_u32_e32 v6, 1, v3
	v_cmp_ge_u32_e32 vcc, v5, v4
	v_add_u32_e32 v5, 1, v7
	s_nop 0
	v_cndmask_b32_e32 v3, v3, v6, vcc
	v_mul_lo_u32 v6, v4, v3
	v_add_u32_e32 v4, v6, v4
	v_cmp_ne_u32_e32 vcc, v5, v4
	s_and_saveexec_b64 s[2:3], vcc
	s_xor_b64 s[12:13], exec, s[2:3]
	s_cbranch_execz .LBB0_293
	s_waitcnt lgkmcnt(0)
	buffer_inv sc1
	global_load_dword v2, v1, s[10:11] offset:1024 sc1
	s_add_u32 s22, s10, 0x2400
	s_addc_u32 s23, s11, 0
	s_waitcnt vmcnt(0)
	v_cmp_eq_u32_e32 vcc, v2, v3
	s_and_saveexec_b64 s[14:15], vcc
	s_cbranch_execz .LBB0_292
	s_add_u32 s18, s8, 0xfc9c200
	s_addc_u32 s19, s9, 0
	s_mov_b32 s2, 1
	s_mov_b64 s[24:25], 0
	s_branch .LBB0_283

; DI unsigned xb_ld(unsigned* p) { return __hip_atomic_load(p, __ATOMIC_RELAXED, __HIP_MEMORY_SCOPE_AGENT); }
; DI unsigned xb_add(unsigned* p, unsigned v) { return __hip_atomic_fetch_add(p, v, __ATOMIC_RELAXED, __HIP_MEMORY_SCOPE_AGENT); }
; #define XB_SPIN(cond, bar) do { unsigned _sp = 0; while (cond) { __builtin_amdgcn_s_sleep(1); \
;     if ((++_sp & 255u) == 0u) { if (xb_ld(&(bar)[XB_TMO])) break; if (_sp > XB_SPIN_CAP) { atomicAdd(&(bar)[XB_TMO], 1u); break; } } } } while (0)
; DI void xcd_barrier(const XcdBarrier& b) {
;     ...
;     if (old + 1u == (gen + 1u) * nloc) {
;       __builtin_amdgcn_fence(__ATOMIC_RELEASE, "agent");
;       asm volatile("s_waitcnt vmcnt(0)" ::: "memory");
;       const unsigned og = xb_add(&bar[XB_TOP], 1u);
;       const unsigned tg = og / nx;
;       if (og + 1u == (tg + 1u) * nx) xb_add(&bar[XB_TOPGEN], 1u);
;       else XB_SPIN(xb_ld(&bar[XB_TOPGEN]) == tg, bar);
;       __builtin_amdgcn_fence(__ATOMIC_ACQUIRE, "agent");
;       xb_add(&bar[XB_XGEN(b.x)], 1u);
;       asm volatile("s_waitcnt vmcnt(0)" ::: "memory");
;     } else {
;       XB_SPIN(xb_ld(&bar[XB_XGEN(b.x)]) == gen, bar);
;       __builtin_amdgcn_fence(__ATOMIC_ACQUIRE, "agent");
;       asm volatile("s_waitcnt vmcnt(0)" ::: "memory");
.LBB0_292:
	s_or_b64 exec, exec, s[14:15]
	s_waitcnt vmcnt(0)
	s_waitcnt vmcnt(0)
.LBB0_293:
	s_andn2_saveexec_b64 s[2:3], s[12:13]
	s_cbranch_execz .LBB0_313
	s_mov_b64 s[12:13], exec
	buffer_inv sc1
	buffer_wbl2 sc1
	s_waitcnt lgkmcnt(0)
	s_waitcnt vmcnt(0)
	v_mbcnt_lo_u32_b32 v3, s12, 0
	v_mbcnt_hi_u32_b32 v3, s13, v3
	v_cmp_eq_u32_e32 vcc, 0, v3
	s_and_saveexec_b64 s[14:15], vcc
	s_cbranch_execz .LBB0_296
	s_bcnt1_i32_b64 s2, s[12:13]
	v_mov_b32_e32 v4, s2
	v_mov_b32_e32 v5, 0xfc9f000
	global_atomic_add v4, v5, v4, s[8:9] offset:1024 sc0

; DI unsigned xb_add(unsigned* p, unsigned v) { return __hip_atomic_fetch_add(p, v, __ATOMIC_RELAXED, __HIP_MEMORY_SCOPE_AGENT); }
; DI void xcd_barrier(const XcdBarrier& b) {
;     ...
;       __builtin_amdgcn_fence(__ATOMIC_ACQUIRE, "agent");
;       xb_add(&bar[XB_XGEN(b.x)], 1u);
.LBB0_310:
	s_or_b64 exec, exec, s[8:9]
	s_mov_b64 s[8:9], exec
	v_mbcnt_lo_u32_b32 v2, s8, 0
	v_mbcnt_hi_u32_b32 v2, s9, v2
	v_cmp_eq_u32_e32 vcc, 0, v2
	s_waitcnt vmcnt(0)
	s_and_saveexec_b64 s[12:13], vcc
	s_cbranch_execz .LBB0_312
	s_bcnt1_i32_b64 s2, s[8:9]
	v_mov_b32_e32 v2, s2
	global_atomic_add v1, v2, s[10:11] offset:1024

; DI unsigned xb_ld(unsigned* p) { return __hip_atomic_load(p, __ATOMIC_RELAXED, __HIP_MEMORY_SCOPE_AGENT); }
; DI unsigned xb_add(unsigned* p, unsigned v) { return __hip_atomic_fetch_add(p, v, __ATOMIC_RELAXED, __HIP_MEMORY_SCOPE_AGENT); }
; #define XB_SPIN(cond, bar) do { unsigned _sp = 0; while (cond) { __builtin_amdgcn_s_sleep(1); \
;     if ((++_sp & 255u) == 0u) { if (xb_ld(&(bar)[XB_TMO])) break; if (_sp > XB_SPIN_CAP) { atomicAdd(&(bar)[XB_TMO], 1u); break; } } } } while (0)
; DI void xcd_barrier(const XcdBarrier& b) {
;     ...
;     const unsigned old = xb_add(&bar[XB_XSUB(b.x)], 1u);
;     const unsigned gen = old / nloc;
;     if (old + 1u == (gen + 1u) * nloc) {
;       __builtin_amdgcn_fence(__ATOMIC_RELEASE, "agent");
;       asm volatile("s_waitcnt vmcnt(0)" ::: "memory");
;       const unsigned og = xb_add(&bar[XB_TOP], 1u);
;       const unsigned tg = og / nx;
;       if (og + 1u == (tg + 1u) * nx) xb_add(&bar[XB_TOPGEN], 1u);
;       else XB_SPIN(xb_ld(&bar[XB_TOPGEN]) == tg, bar);
;       __builtin_amdgcn_fence(__ATOMIC_ACQUIRE, "agent");
;       xb_add(&bar[XB_XGEN(b.x)], 1u);
;       asm volatile("s_waitcnt vmcnt(0)" ::: "memory");
;     } else {
;       XB_SPIN(xb_ld(&bar[XB_XGEN(b.x)]) == gen, bar);
;       __builtin_amdgcn_fence(__ATOMIC_ACQUIRE, "agent");
;       asm volatile("s_waitcnt vmcnt(0)" ::: "memory");
.LBB0_875:
	s_or_b64 exec, exec, s[14:15]
	v_cvt_f32_u32_e32 v6, v4
	s_waitcnt vmcnt(0)
	v_readfirstlane_b32 s2, v5
	v_sub_u32_e32 v5, 0, v4
	v_rcp_iflag_f32_e32 v6, v6
	v_add_u32_e32 v7, s2, v3
	v_mul_f32_e32 v6, 0x4f7ffffe, v6
	v_cvt_u32_f32_e32 v6, v6
	v_mul_lo_u32 v3, v5, v6
	v_mul_hi_u32 v3, v6, v3
	v_add_u32_e32 v3, v6, v3
	v_mul_hi_u32 v3, v7, v3
	v_mul_lo_u32 v5, v3, v4
	v_sub_u32_e32 v5, v7, v5
	v_add_u32_e32 v6, 1, v3
	v_cmp_ge_u32_e32 vcc, v5, v4
	s_nop 1
	v_cndmask_b32_e32 v3, v3, v6, vcc
	v_sub_u32_e32 v6, v5, v4
	v_cndmask_b32_e32 v5, v5, v6, vcc
	v_add_u32_e32 v6, 1, v3
	v_cmp_ge_u32_e32 vcc, v5, v4
	v_add_u32_e32 v5, 1, v7
	s_nop 0
	v_cndmask_b32_e32 v3, v3, v6, vcc
	v_mul_lo_u32 v6, v4, v3
	v_add_u32_e32 v4, v6, v4
	v_cmp_ne_u32_e32 vcc, v5, v4
	s_and_saveexec_b64 s[2:3], vcc
	s_xor_b64 s[12:13], exec, s[2:3]
	s_cbranch_execz .LBB0_889
	s_waitcnt lgkmcnt(0)
	buffer_inv sc1
	global_load_dword v2, v1, s[10:11] offset:1024 sc1
	s_add_u32 s18, s10, 0x2400
	s_addc_u32 s19, s11, 0
	s_waitcnt vmcnt(0)
	v_cmp_eq_u32_e32 vcc, v2, v3
	s_and_saveexec_b64 s[14:15], vcc
	s_cbranch_execz .LBB0_888
	s_add_u32 s16, s8, 0xfc9c200
	s_addc_u32 s17, s9, 0
	s_mov_b32 s2, 1
	s_mov_b64 s[22:23], 0
	s_branch .LBB0_879

; DI unsigned xb_ld(unsigned* p) { return __hip_atomic_load(p, __ATOMIC_RELAXED, __HIP_MEMORY_SCOPE_AGENT); }
; DI unsigned xb_add(unsigned* p, unsigned v) { return __hip_atomic_fetch_add(p, v, __ATOMIC_RELAXED, __HIP_MEMORY_SCOPE_AGENT); }
; #define XB_SPIN(cond, bar) do { unsigned _sp = 0; while (cond) { __builtin_amdgcn_s_sleep(1); \
;     if ((++_sp & 255u) == 0u) { if (xb_ld(&(bar)[XB_TMO])) break; if (_sp > XB_SPIN_CAP) { atomicAdd(&(bar)[XB_TMO], 1u); break; } } } } while (0)
; DI void xcd_barrier(const XcdBarrier& b) {
;     ...
;     const unsigned old = xb_add(&bar[XB_XSUB(b.x)], 1u);
;     const unsigned gen = old / nloc;
;     if (old + 1u == (gen + 1u) * nloc) {
;       __builtin_amdgcn_fence(__ATOMIC_RELEASE, "agent");
;       asm volatile("s_waitcnt vmcnt(0)" ::: "memory");
;       const unsigned og = xb_add(&bar[XB_TOP], 1u);
;       const unsigned tg = og / nx;
;       if (og + 1u == (tg + 1u) * nx) xb_add(&bar[XB_TOPGEN], 1u);
;       else XB_SPIN(xb_ld(&bar[XB_TOPGEN]) == tg, bar);
;       __builtin_amdgcn_fence(__ATOMIC_ACQUIRE, "agent");
;       xb_add(&bar[XB_XGEN(b.x)], 1u);
;       asm volatile("s_waitcnt vmcnt(0)" ::: "memory");
;     } else {
;       XB_SPIN(xb_ld(&bar[XB_XGEN(b.x)]) == gen, bar);
;       __builtin_amdgcn_fence(__ATOMIC_ACQUIRE, "agent");
;       asm volatile("s_waitcnt vmcnt(0)" ::: "memory");
.LBB0_1819:
	s_or_b64 exec, exec, s[18:19]
	v_cvt_f32_u32_e32 v6, v4
	s_waitcnt vmcnt(0)
	v_readfirstlane_b32 s2, v5
	v_sub_u32_e32 v5, 0, v4
	v_rcp_iflag_f32_e32 v6, v6
	v_add_u32_e32 v7, s2, v3
	v_mul_f32_e32 v6, 0x4f7ffffe, v6
	v_cvt_u32_f32_e32 v6, v6
	v_mul_lo_u32 v3, v5, v6
	v_mul_hi_u32 v3, v6, v3
	v_add_u32_e32 v3, v6, v3
	v_mul_hi_u32 v3, v7, v3
	v_mul_lo_u32 v5, v3, v4
	v_sub_u32_e32 v5, v7, v5
	v_add_u32_e32 v6, 1, v3
	v_cmp_ge_u32_e32 vcc, v5, v4
	s_nop 1
	v_cndmask_b32_e32 v3, v3, v6, vcc
	v_sub_u32_e32 v6, v5, v4
	v_cndmask_b32_e32 v5, v5, v6, vcc
	v_add_u32_e32 v6, 1, v3
	v_cmp_ge_u32_e32 vcc, v5, v4
	v_add_u32_e32 v5, 1, v7
	s_nop 0
	v_cndmask_b32_e32 v3, v3, v6, vcc
	v_mul_lo_u32 v6, v4, v3
	v_add_u32_e32 v4, v6, v4
	v_cmp_ne_u32_e32 vcc, v5, v4
	s_and_saveexec_b64 s[2:3], vcc
	s_xor_b64 s[16:17], exec, s[2:3]
	s_cbranch_execz .LBB0_1833
	s_waitcnt lgkmcnt(0)
	buffer_inv sc1
	global_load_dword v2, v1, s[14:15] offset:1024 sc1
	s_add_u32 s24, s14, 0x2400
	s_addc_u32 s25, s15, 0
	s_waitcnt vmcnt(0)
	v_cmp_eq_u32_e32 vcc, v2, v3
	s_and_saveexec_b64 s[18:19], vcc
	s_cbranch_execz .LBB0_1832
	s_add_u32 s22, s12, 0xfc9c200
	s_addc_u32 s23, s13, 0
	s_mov_b32 s2, 1
	s_mov_b64 s[26:27], 0
	s_branch .LBB0_1823

; DI unsigned xb_ld(unsigned* p) { return __hip_atomic_load(p, __ATOMIC_RELAXED, __HIP_MEMORY_SCOPE_AGENT); }
; DI unsigned xb_add(unsigned* p, unsigned v) { return __hip_atomic_fetch_add(p, v, __ATOMIC_RELAXED, __HIP_MEMORY_SCOPE_AGENT); }
; #define XB_SPIN(cond, bar) do { unsigned _sp = 0; while (cond) { __builtin_amdgcn_s_sleep(1); \
;     if ((++_sp & 255u) == 0u) { if (xb_ld(&(bar)[XB_TMO])) break; if (_sp > XB_SPIN_CAP) { atomicAdd(&(bar)[XB_TMO], 1u); break; } } } } while (0)
; DI void xcd_barrier(const XcdBarrier& b) {
;     ...
;     if (old + 1u == (gen + 1u) * nloc) {
;       __builtin_amdgcn_fence(__ATOMIC_RELEASE, "agent");
;       asm volatile("s_waitcnt vmcnt(0)" ::: "memory");
;       const unsigned og = xb_add(&bar[XB_TOP], 1u);
;       const unsigned tg = og / nx;
;       if (og + 1u == (tg + 1u) * nx) xb_add(&bar[XB_TOPGEN], 1u);
;       else XB_SPIN(xb_ld(&bar[XB_TOPGEN]) == tg, bar);
;       __builtin_amdgcn_fence(__ATOMIC_ACQUIRE, "agent");
;       xb_add(&bar[XB_XGEN(b.x)], 1u);
;       asm volatile("s_waitcnt vmcnt(0)" ::: "memory");
;     } else {
;       XB_SPIN(xb_ld(&bar[XB_XGEN(b.x)]) == gen, bar);
;       __builtin_amdgcn_fence(__ATOMIC_ACQUIRE, "agent");
;       asm volatile("s_waitcnt vmcnt(0)" ::: "memory");
.LBB0_1832:
	s_or_b64 exec, exec, s[18:19]
	s_waitcnt vmcnt(0)
	s_waitcnt vmcnt(0)
.LBB0_1833:
	s_andn2_saveexec_b64 s[2:3], s[16:17]
	s_cbranch_execz .LBB0_1853
	s_mov_b64 s[16:17], exec
	buffer_inv sc1
	buffer_wbl2 sc1
	s_waitcnt lgkmcnt(0)
	s_waitcnt vmcnt(0)
	v_mbcnt_lo_u32_b32 v3, s16, 0
	v_mbcnt_hi_u32_b32 v3, s17, v3
	v_cmp_eq_u32_e32 vcc, 0, v3
	s_and_saveexec_b64 s[18:19], vcc
	s_cbranch_execz .LBB0_1836
	s_bcnt1_i32_b64 s2, s[16:17]
	v_mov_b32_e32 v4, s2
	v_mov_b32_e32 v5, 0xfc9f000
	global_atomic_add v4, v5, v4, s[12:13] offset:1024 sc0

; DI unsigned xb_add(unsigned* p, unsigned v) { return __hip_atomic_fetch_add(p, v, __ATOMIC_RELAXED, __HIP_MEMORY_SCOPE_AGENT); }
; DI void xcd_barrier(const XcdBarrier& b) {
;     ...
;       __builtin_amdgcn_fence(__ATOMIC_ACQUIRE, "agent");
;       xb_add(&bar[XB_XGEN(b.x)], 1u);
.LBB0_1850:
	s_or_b64 exec, exec, s[12:13]
	s_mov_b64 s[12:13], exec
	v_mbcnt_lo_u32_b32 v2, s12, 0
	v_mbcnt_hi_u32_b32 v2, s13, v2
	v_cmp_eq_u32_e32 vcc, 0, v2
	s_waitcnt vmcnt(0)
	s_and_saveexec_b64 s[16:17], vcc
	s_cbranch_execz .LBB0_1852
	s_bcnt1_i32_b64 s2, s[12:13]
	v_mov_b32_e32 v2, s2
	global_atomic_add v1, v2, s[14:15] offset:1024

; DI unsigned xb_add(unsigned* p, unsigned v) { return __hip_atomic_fetch_add(p, v, __ATOMIC_RELAXED, __HIP_MEMORY_SCOPE_AGENT); }
; DI void xcd_barrier(const XcdBarrier& b) {
;     ...
;     if (old + 1u == (gen + 1u) * nloc) {
;       __builtin_amdgcn_fence(__ATOMIC_RELEASE, "agent");
;       asm volatile("s_waitcnt vmcnt(0)" ::: "memory");
;       const unsigned og = xb_add(&bar[XB_TOP], 1u);
.LBB0_2054:
	s_mov_b64 s[12:13], exec
	buffer_inv sc1
	buffer_wbl2 sc1
	s_waitcnt lgkmcnt(0)
	s_waitcnt vmcnt(0)
	v_mbcnt_lo_u32_b32 v3, s12, 0
	v_mbcnt_hi_u32_b32 v3, s13, v3
	v_cmp_eq_u32_e32 vcc, 0, v3
	s_and_saveexec_b64 s[14:15], vcc
	s_cbranch_execz .LBB0_2056
	s_bcnt1_i32_b64 s2, s[12:13]
	v_mov_b32_e32 v4, s2
	v_mov_b32_e32 v5, 0xfc9f000
	global_atomic_add v4, v5, v4, s[8:9] offset:1024 sc0

; DI unsigned xb_add(unsigned* p, unsigned v) { return __hip_atomic_fetch_add(p, v, __ATOMIC_RELAXED, __HIP_MEMORY_SCOPE_AGENT); }
; DI void xcd_barrier(const XcdBarrier& b) {
;     ...
;       __builtin_amdgcn_fence(__ATOMIC_ACQUIRE, "agent");
;       xb_add(&bar[XB_XGEN(b.x)], 1u);
.LBB0_2070:
	s_or_b64 exec, exec, s[8:9]
	s_mov_b64 s[8:9], exec
	v_mbcnt_lo_u32_b32 v2, s8, 0
	v_mbcnt_hi_u32_b32 v2, s9, v2
	v_cmp_eq_u32_e32 vcc, 0, v2
	s_waitcnt vmcnt(0)
	s_and_saveexec_b64 s[12:13], vcc
	s_cbranch_execnz .LBB0_2071
	s_getpc_b64 s[98:99]
